# hyena conv'd-v tile build: all loads of a half issued before one wait (halo loads unconditional + masked), no per-halo vmcnt(0)
# speedup vs baseline: 1.0467x; 1.0091x over previous
.LBB0_449:
	s_ashr_i32 s41, s40, 31
	s_add_i32 s50, s40, 0x200
	s_lshl_b64 s[2:3], s[40:41], 13
	s_ashr_i32 s51, s50, 31
	v_lshl_add_u64 v[0:1], v[138:139], 0, s[2:3]
	s_lshl_b64 s[2:3], s[50:51], 13
	s_lshl_b64 s[42:43], s[40:41], 16
	s_lshl_b64 s[58:59], s[40:41], 2
	s_add_u32 s44, s54, s58
	s_addc_u32 s45, s55, s59
	v_lshl_add_u64 v[2:3], v[138:139], 0, s[2:3]
	s_add_u32 s48, s56, s58
	global_load_dwordx4 v[8:11], v[0:1], off
	s_nop 0
	global_load_dwordx4 v[2:5], v[2:3], off
	s_barrier
	s_addc_u32 s49, s57, s59
	global_load_dword v0, v141, s[44:45]
	global_load_dword v6, v156, s[44:45] offset:2048
	global_load_dword v12, v141, s[48:49]
	global_load_dword v14, v157, s[44:45]
	s_mov_b64 s[60:61], -1
	v_lshl_add_u64 v[16:17], v[142:143], 0, s[42:43]
	s_mov_b32 s2, 0
	s_branch .LBB0_451
.LBB0_450:
	s_waitcnt vmcnt(0)
	v_mov_b32_e32 v1, v0
	v_mov_b32_e32 v7, v6
	v_mov_b32_e32 v13, v12
	v_mov_b32_e32 v15, v14
	v_lshlrev_b32_e32 v24, 16, v24
	v_lshlrev_b32_e32 v23, 16, v23
	v_cndmask_b32_e64 v24, 0, v24, s[0:1]
	v_cndmask_b32_e64 v23, 0, v23, s[16:17]
	v_lshlrev_b32_e32 v34, 16, v34
	v_lshlrev_b32_e32 v33, 16, v33
	v_cndmask_b32_e64 v34, 0, v34, s[0:1]
	v_cndmask_b32_e64 v33, 0, v33, s[16:17]
	v_lshlrev_b32_e32 v44, 16, v44
	v_lshlrev_b32_e32 v41, 16, v41
	v_cndmask_b32_e64 v44, 0, v44, s[0:1]
	v_cndmask_b32_e64 v41, 0, v41, s[16:17]
	v_lshlrev_b32_e32 v54, 16, v54
	v_lshlrev_b32_e32 v51, 16, v51
	v_cndmask_b32_e64 v54, 0, v54, s[0:1]
	v_cndmask_b32_e64 v51, 0, v51, s[16:17]
	v_lshlrev_b32_e32 v62, 16, v62
	v_lshlrev_b32_e32 v59, 16, v59
	v_cndmask_b32_e64 v62, 0, v62, s[0:1]
	v_cndmask_b32_e64 v59, 0, v59, s[16:17]
	v_lshlrev_b32_e32 v72, 16, v72
	v_lshlrev_b32_e32 v71, 16, v71
	v_cndmask_b32_e64 v72, 0, v72, s[0:1]
	v_cndmask_b32_e64 v71, 0, v71, s[16:17]
	v_lshlrev_b32_e32 v78, 16, v78
	v_lshlrev_b32_e32 v77, 16, v77
	v_cndmask_b32_e64 v78, 0, v78, s[0:1]
	v_cndmask_b32_e64 v77, 0, v77, s[16:17]
	v_lshlrev_b32_e32 v66, 16, v66
	v_lshlrev_b32_e32 v61, 16, v61
	v_cndmask_b32_e64 v66, 0, v66, s[0:1]
	v_cndmask_b32_e64 v61, 0, v61, s[16:17]
	v_lshlrev_b32_e32 v79, 16, v80
	v_and_b32_e32 v80, 0xffff0000, v80
	v_lshlrev_b32_e32 v82, 16, v81
	v_pk_fma_f32 v[84:85], v[0:1], v[78:79], v[12:13]
	v_mov_b32_e32 v78, v79
	v_mov_b32_e32 v79, v80
	v_and_b32_e32 v83, 0xffff0000, v81
	v_mov_b32_e32 v81, v82
	v_pk_fma_f32 v[78:79], v[6:7], v[78:79], v[84:85]
	v_mov_b32_e32 v76, v83
	v_pk_fma_f32 v[78:79], v[14:15], v[80:81], v[78:79]
	v_pk_fma_f32 v[80:81], v[0:1], v[80:81], v[12:13]
	v_lshlrev_b32_e32 v73, 16, v74
	v_pk_fma_f32 v[80:81], v[6:7], v[82:83], v[80:81]
	v_and_b32_e32 v74, 0xffff0000, v74
	v_pk_fma_f32 v[76:77], v[14:15], v[76:77], v[80:81]
	v_lshlrev_b32_e32 v80, 16, v75
	v_pk_fma_f32 v[82:83], v[0:1], v[72:73], v[12:13]
	v_mov_b32_e32 v72, v73
	v_mov_b32_e32 v73, v74
	v_and_b32_e32 v81, 0xffff0000, v75
	v_mov_b32_e32 v75, v80
	v_pk_fma_f32 v[72:73], v[6:7], v[72:73], v[82:83]
	v_mov_b32_e32 v70, v81
	v_pk_fma_f32 v[72:73], v[14:15], v[74:75], v[72:73]
	v_pk_fma_f32 v[74:75], v[0:1], v[74:75], v[12:13]
	v_lshlrev_b32_e32 v63, 16, v64
	v_pk_fma_f32 v[74:75], v[6:7], v[80:81], v[74:75]
	v_and_b32_e32 v64, 0xffff0000, v64
	v_pk_fma_f32 v[70:71], v[14:15], v[70:71], v[74:75]
	v_lshlrev_b32_e32 v74, 16, v65
	v_pk_fma_f32 v[80:81], v[0:1], v[62:63], v[12:13]
	v_mov_b32_e32 v62, v63
	v_mov_b32_e32 v63, v64
	v_and_b32_e32 v75, 0xffff0000, v65
	v_mov_b32_e32 v65, v74
	v_pk_fma_f32 v[62:63], v[6:7], v[62:63], v[80:81]
	v_mov_b32_e32 v58, v75
	v_pk_fma_f32 v[62:63], v[14:15], v[64:65], v[62:63]
	v_pk_fma_f32 v[64:65], v[0:1], v[64:65], v[12:13]
	v_lshlrev_b32_e32 v55, 16, v56
	v_pk_fma_f32 v[64:65], v[6:7], v[74:75], v[64:65]
	v_and_b32_e32 v56, 0xffff0000, v56
	v_pk_fma_f32 v[58:59], v[14:15], v[58:59], v[64:65]
	v_lshlrev_b32_e32 v64, 16, v57
	v_pk_fma_f32 v[74:75], v[0:1], v[54:55], v[12:13]
	v_mov_b32_e32 v54, v55
	v_mov_b32_e32 v55, v56
	v_and_b32_e32 v65, 0xffff0000, v57
	v_mov_b32_e32 v57, v64
	v_pk_fma_f32 v[54:55], v[6:7], v[54:55], v[74:75]
	v_mov_b32_e32 v50, v65
	v_pk_fma_f32 v[54:55], v[14:15], v[56:57], v[54:55]
	v_pk_fma_f32 v[56:57], v[0:1], v[56:57], v[12:13]
	v_lshlrev_b32_e32 v45, 16, v46
	v_pk_fma_f32 v[56:57], v[6:7], v[64:65], v[56:57]
	v_and_b32_e32 v46, 0xffff0000, v46
	v_pk_fma_f32 v[50:51], v[14:15], v[50:51], v[56:57]
	v_lshlrev_b32_e32 v56, 16, v47
	v_pk_fma_f32 v[64:65], v[0:1], v[44:45], v[12:13]
	v_mov_b32_e32 v44, v45
	v_mov_b32_e32 v45, v46
	v_and_b32_e32 v57, 0xffff0000, v47
	v_mov_b32_e32 v47, v56
	v_pk_fma_f32 v[44:45], v[6:7], v[44:45], v[64:65]
	v_mov_b32_e32 v40, v57
	v_pk_fma_f32 v[44:45], v[14:15], v[46:47], v[44:45]
	v_pk_fma_f32 v[46:47], v[0:1], v[46:47], v[12:13]
	v_lshlrev_b32_e32 v35, 16, v36
	v_pk_fma_f32 v[46:47], v[6:7], v[56:57], v[46:47]
	v_and_b32_e32 v36, 0xffff0000, v36
	v_pk_fma_f32 v[40:41], v[14:15], v[40:41], v[46:47]
	v_lshlrev_b32_e32 v46, 16, v37
	v_pk_fma_f32 v[56:57], v[0:1], v[34:35], v[12:13]
	v_mov_b32_e32 v34, v35
	v_mov_b32_e32 v35, v36
	v_and_b32_e32 v47, 0xffff0000, v37
	v_mov_b32_e32 v37, v46
	v_pk_fma_f32 v[34:35], v[6:7], v[34:35], v[56:57]
	v_mov_b32_e32 v32, v47
	v_pk_fma_f32 v[34:35], v[14:15], v[36:37], v[34:35]
	v_pk_fma_f32 v[36:37], v[0:1], v[36:37], v[12:13]
	v_lshlrev_b32_e32 v25, 16, v26
	v_pk_fma_f32 v[36:37], v[6:7], v[46:47], v[36:37]
	v_and_b32_e32 v26, 0xffff0000, v26
	v_pk_fma_f32 v[32:33], v[14:15], v[32:33], v[36:37]
	v_lshlrev_b32_e32 v36, 16, v27
	v_pk_fma_f32 v[46:47], v[0:1], v[24:25], v[12:13]
	v_mov_b32_e32 v24, v25
	v_mov_b32_e32 v25, v26
	v_and_b32_e32 v37, 0xffff0000, v27
	v_mov_b32_e32 v27, v36
	v_pk_fma_f32 v[24:25], v[6:7], v[24:25], v[46:47]
	v_mov_b32_e32 v22, v37
	v_pk_fma_f32 v[24:25], v[14:15], v[26:27], v[24:25]
	v_pk_fma_f32 v[26:27], v[0:1], v[26:27], v[12:13]
	v_cvt_pk_bf16_f32 v24, v24, v25
	v_pk_fma_f32 v[26:27], v[6:7], v[36:37], v[26:27]
	v_mad_i32_i24 v18, v18, s64, v151
	v_pk_fma_f32 v[22:23], v[14:15], v[22:23], v[26:27]
	s_waitcnt vmcnt(0)
	v_lshlrev_b32_e32 v67, 16, v68
	v_cvt_pk_bf16_f32 v25, v22, v23
	v_and_b32_e32 v26, 0xffff0000, v68
	ds_write_b64 v18, v[24:25]
	v_cvt_pk_bf16_f32 v18, v34, v35
	v_cvt_pk_bf16_f32 v19, v32, v33
	v_mad_i32_i24 v20, v20, s64, v151
	v_lshlrev_b32_e32 v36, 16, v69
	v_pk_fma_f32 v[46:47], v[0:1], v[66:67], v[12:13]
	v_mov_b32_e32 v56, v67
	v_mov_b32_e32 v57, v26
	ds_write_b64 v20, v[18:19]
	v_cvt_pk_bf16_f32 v18, v44, v45
	v_cvt_pk_bf16_f32 v19, v40, v41
	v_mad_i32_i24 v20, v28, s64, v151
	v_mov_b32_e32 v27, v36
	v_pk_fma_f32 v[46:47], v[6:7], v[56:57], v[46:47]
	ds_write_b64 v20, v[18:19]
	v_cvt_pk_bf16_f32 v18, v54, v55
	v_cvt_pk_bf16_f32 v19, v50, v51
	v_mad_i32_i24 v20, v30, s64, v151
	v_and_b32_e32 v37, 0xffff0000, v69
	v_pk_fma_f32 v[46:47], v[14:15], v[26:27], v[46:47]
	v_pk_fma_f32 v[26:27], v[0:1], v[26:27], v[12:13]
	ds_write_b64 v20, v[18:19]
	v_cvt_pk_bf16_f32 v18, v62, v63
	v_cvt_pk_bf16_f32 v19, v58, v59
	v_mad_i32_i24 v20, v38, s64, v151
	v_pk_fma_f32 v[26:27], v[6:7], v[36:37], v[26:27]
	v_mov_b32_e32 v60, v37
	ds_write_b64 v20, v[18:19]
	v_cvt_pk_bf16_f32 v18, v72, v73
	v_cvt_pk_bf16_f32 v19, v70, v71
	v_mad_i32_i24 v20, v42, s64, v151
	s_xor_b64 s[62:63], s[60:61], -1
	v_pk_fma_f32 v[26:27], v[14:15], v[60:61], v[26:27]
	ds_write_b64 v20, v[18:19]
	v_cvt_pk_bf16_f32 v18, v78, v79
	v_cvt_pk_bf16_f32 v19, v76, v77
	v_mad_i32_i24 v20, v48, s64, v151
	ds_write_b64 v20, v[18:19]
	v_cvt_pk_bf16_f32 v18, v46, v47
	v_cvt_pk_bf16_f32 v19, v26, v27
	v_mad_i32_i24 v20, v52, s64, v151
	s_movk_i32 s2, 0x1000
	s_mov_b64 s[60:61], 0
	s_and_b64 vcc, exec, s[62:63]
	ds_write_b64 v20, v[18:19]
	s_cbranch_vccnz .LBB0_483
.LBB0_451:
	v_add_u32_e32 v22, s2, v150
	v_ashrrev_i32_e32 v18, 9, v22
	v_ashrrev_i32_e32 v19, 31, v18
	v_lshlrev_b64 v[20:21], 12, v[18:19]
	v_lshl_add_u64 v[20:21], v[16:17], 0, v[20:21]
	global_load_dwordx2 v[26:27], v[20:21], off
	global_load_ushort v24, v[20:21], off offset:-2
	global_load_ushort v23, v[20:21], off offset:8
	v_add_u32_e32 v19, 0x200, v22
	v_ashrrev_i32_e32 v20, 9, v19
	v_ashrrev_i32_e32 v21, 31, v20
	v_lshlrev_b64 v[28:29], 12, v[20:21]
	v_lshl_add_u64 v[28:29], v[16:17], 0, v[28:29]
	global_load_dwordx2 v[36:37], v[28:29], off
	global_load_ushort v34, v[28:29], off offset:-2
	global_load_ushort v33, v[28:29], off offset:8
	v_add_u32_e32 v19, 0x400, v22
	v_ashrrev_i32_e32 v28, 9, v19
	v_ashrrev_i32_e32 v29, 31, v28
	v_lshlrev_b64 v[30:31], 12, v[28:29]
	v_lshl_add_u64 v[30:31], v[16:17], 0, v[30:31]
	global_load_dwordx2 v[46:47], v[30:31], off
	global_load_ushort v44, v[30:31], off offset:-2
	global_load_ushort v41, v[30:31], off offset:8
	v_add_u32_e32 v19, 0x600, v22
	v_ashrrev_i32_e32 v30, 9, v19
	v_ashrrev_i32_e32 v31, 31, v30
	v_lshlrev_b64 v[38:39], 12, v[30:31]
	v_lshl_add_u64 v[38:39], v[16:17], 0, v[38:39]
	global_load_dwordx2 v[56:57], v[38:39], off
	global_load_ushort v54, v[38:39], off offset:-2
	global_load_ushort v51, v[38:39], off offset:8
	v_add_u32_e32 v19, 0x800, v22
	v_ashrrev_i32_e32 v38, 9, v19
	v_ashrrev_i32_e32 v39, 31, v38
	v_lshlrev_b64 v[42:43], 12, v[38:39]
	v_lshl_add_u64 v[42:43], v[16:17], 0, v[42:43]
	global_load_dwordx2 v[64:65], v[42:43], off
	global_load_ushort v62, v[42:43], off offset:-2
	global_load_ushort v59, v[42:43], off offset:8
	v_add_u32_e32 v19, 0xa00, v22
	v_ashrrev_i32_e32 v42, 9, v19
	v_ashrrev_i32_e32 v43, 31, v42
	v_lshlrev_b64 v[48:49], 12, v[42:43]
	v_lshl_add_u64 v[48:49], v[16:17], 0, v[48:49]
	global_load_dwordx2 v[74:75], v[48:49], off
	global_load_ushort v72, v[48:49], off offset:-2
	global_load_ushort v71, v[48:49], off offset:8
	v_add_u32_e32 v19, 0xc00, v22
	v_ashrrev_i32_e32 v48, 9, v19
	v_ashrrev_i32_e32 v49, 31, v48
	v_lshlrev_b64 v[52:53], 12, v[48:49]
	v_lshl_add_u64 v[52:53], v[16:17], 0, v[52:53]
	global_load_dwordx2 v[80:81], v[52:53], off
	global_load_ushort v78, v[52:53], off offset:-2
	global_load_ushort v77, v[52:53], off offset:8
	v_add_u32_e32 v19, 0xe00, v22
	v_ashrrev_i32_e32 v52, 9, v19
	v_ashrrev_i32_e32 v53, 31, v52
	v_lshlrev_b64 v[60:61], 12, v[52:53]
	v_lshl_add_u64 v[82:83], v[16:17], 0, v[60:61]
	global_load_dwordx2 v[68:69], v[82:83], off
	global_load_ushort v66, v[82:83], off offset:-2
	global_load_ushort v61, v[82:83], off offset:8
	s_branch .LBB0_450
